# dilated unit: row-max and row-sum cross-half exchanges by v_permlane32_swap instead of ds_bpermute (lever 7)
# baseline (speedup 1.0000x reference)
; #define LAS __attribute__((address_space(3)))
; DI float ex2(float x) { return __builtin_amdgcn_exp2f(x); }
; DI int crow(int i, int hh) { return (i & 3) + 8 * (i >> 2) + 4 * hh; }
; #define MFMA32(a, b, c) __builtin_amdgcn_mfma_f32_32x32x16_bf16((a), (b), (c), 0, 0, 0)
; #define VFRAG2(off) __builtin_shufflevector(*(const LAS s16x4*)(vp + (((off) + 4 * hh) ^ sw)), *(const LAS s16x4*)(vp + (((off) + 8 + 4 * hh) ^ sw)), 0, 1, 2, 3, 4, 5, 6, 7)
; DI void attn_dil_unit(LAS unsigned char* lds, const AttnArgs a) {
;     ...
;     float mx = -1e30f;
; #pragma unroll
;     for (int j = 0; j < 5; ++j)
; #pragma unroll
;         for (int i = 0; i < 16; ++i) {
;             const int st = r32 + 128 - 32 * j - crow(i, hh);
;             const int kj = qi - st;
;             const bool valid = (st >= 0) && (st <= 128) && (kj >= 0);
;             float x = sc[j][i] * a.c2 + biasL[min(max(st, 0), 128)];
;             x = valid ? x : -1e30f;
;             sc[j][i] = x; mx = fmaxf(mx, x);
;         }
;     mx = fmaxf(mx, __shfl_xor(mx, 32));
;     float ls = 0.f;
; #pragma unroll
;     for (int j = 0; j < 5; ++j)
; #pragma unroll
;         for (int i = 0; i < 16; ++i) { const float p = (sc[j][i] > -1e29f) ? ex2(sc[j][i] - mx) : 0.f; sc[j][i] = p; ls += p; }
;     const float lt = ls + __shfl_xor(ls, 32);
;     f32x16 o[2];
; #pragma unroll
;     for (int d = 0; d < 2; ++d)
; #pragma unroll
;         for (int i = 0; i < 16; ++i) o[d][i] = 0.f;
; #pragma unroll
;     for (int j = 0; j < 5; ++j) {
;         const bf16x8 pb0 = pack8(sc[j], 0), pb1 = pack8(sc[j], 1);
; #pragma unroll
;         for (int d = 0; d < 2; ++d) {
;             const LAS bf16_t* vp = Vl + (d * 32 + r32) * VLD + 32 * wid + 32 * j;
;             const int sw = (((d * 32 + r32) >> 3) & 7) << 2;
;     ...
;             o[d] = MFMA32(VFRAG2(0), pb0, o[d]);
;             o[d] = MFMA32(VFRAG2(16), pb1, o[d]);
.Ldil_nomask3:
	v_max3_f32 v187, v187, v150, v151
	v_max3_f32 v187, v187, v152, v153
	v_max3_f32 v187, v187, v154, v155
	v_max3_f32 v187, v187, v156, v157
	v_max3_f32 v187, v187, v158, v159
	v_max3_f32 v187, v187, v160, v161
	v_max3_f32 v187, v187, v162, v163
	v_max3_f32 v187, v187, v164, v165
	s_waitcnt lgkmcnt(0)
	v_subrev_u32_e32 v186, 32, v186
	v_fma_f32 v166, v166, s1, v34
	v_fma_f32 v167, v167, s1, v35
	v_fma_f32 v168, v168, s1, v36
	v_fma_f32 v169, v169, s1, v37
	v_fma_f32 v170, v170, s1, v38
	v_fma_f32 v171, v171, s1, v39
	v_fma_f32 v172, v172, s1, v40
	v_fma_f32 v173, v173, s1, v41
	v_fma_f32 v174, v174, s1, v42
	v_fma_f32 v175, v175, s1, v43
	v_fma_f32 v176, v176, s1, v44
	v_fma_f32 v177, v177, s1, v45
	v_fma_f32 v178, v178, s1, v46
	v_fma_f32 v179, v179, s1, v47
	v_fma_f32 v180, v180, s1, v48
	v_fma_f32 v181, v181, s1, v49
	v_sub_u32_e32 v198, 0, v186
	v_sub_u32_e32 v199, 1, v186
	v_sub_u32_e32 v188, 2, v186
	v_sub_u32_e32 v189, 3, v186
	v_cmp_ge_u32_e64 s[6:7], v185, v198
	v_cmp_ge_u32_e64 s[8:9], v185, v199
	v_cmp_ge_u32_e64 s[10:11], v185, v188
	v_cmp_ge_u32_e64 s[12:13], v185, v189
	v_cndmask_b32_e64 v166, v239, v166, s[6:7]
	v_cndmask_b32_e64 v167, v239, v167, s[8:9]
	v_cndmask_b32_e64 v168, v239, v168, s[10:11]
	v_cndmask_b32_e64 v169, v239, v169, s[12:13]
	v_sub_u32_e32 v198, 8, v186
	v_sub_u32_e32 v199, 9, v186
	v_sub_u32_e32 v188, 10, v186
	v_sub_u32_e32 v189, 11, v186
	v_cmp_ge_u32_e64 s[6:7], v185, v198
	v_cmp_ge_u32_e64 s[8:9], v185, v199
	v_cmp_ge_u32_e64 s[10:11], v185, v188
	v_cmp_ge_u32_e64 s[12:13], v185, v189
	v_cndmask_b32_e64 v170, v239, v170, s[6:7]
	v_cndmask_b32_e64 v171, v239, v171, s[8:9]
	v_cndmask_b32_e64 v172, v239, v172, s[10:11]
	v_cndmask_b32_e64 v173, v239, v173, s[12:13]
	v_sub_u32_e32 v198, 16, v186
	v_sub_u32_e32 v199, 17, v186
	v_sub_u32_e32 v188, 18, v186
	v_sub_u32_e32 v189, 19, v186
	v_cmp_ge_u32_e64 s[6:7], v185, v198
	v_cmp_ge_u32_e64 s[8:9], v185, v199
	v_cmp_ge_u32_e64 s[10:11], v185, v188
	v_cmp_ge_u32_e64 s[12:13], v185, v189
	v_cndmask_b32_e64 v174, v239, v174, s[6:7]
	v_cndmask_b32_e64 v175, v239, v175, s[8:9]
	v_cndmask_b32_e64 v176, v239, v176, s[10:11]
	v_cndmask_b32_e64 v177, v239, v177, s[12:13]
	v_sub_u32_e32 v198, 24, v186
	v_sub_u32_e32 v199, 25, v186
	v_sub_u32_e32 v188, 26, v186
	v_sub_u32_e32 v189, 27, v186
	v_cmp_ge_u32_e64 s[6:7], v185, v198
	v_cmp_ge_u32_e64 s[8:9], v185, v199
	v_cmp_ge_u32_e64 s[10:11], v185, v188
	v_cmp_ge_u32_e64 s[12:13], v185, v189
	v_cndmask_b32_e64 v178, v239, v178, s[6:7]
	v_cndmask_b32_e64 v179, v239, v179, s[8:9]
	v_cndmask_b32_e64 v180, v239, v180, s[10:11]
	v_cndmask_b32_e64 v181, v239, v181, s[12:13]
	v_max3_f32 v187, v187, v166, v167
	v_max3_f32 v187, v187, v168, v169
	v_max3_f32 v187, v187, v170, v171
	v_max3_f32 v187, v187, v172, v173
	v_max3_f32 v187, v187, v174, v175
	v_max3_f32 v187, v187, v176, v177
	v_max3_f32 v187, v187, v178, v179
	v_max3_f32 v187, v187, v180, v181
	v_mov_b32_e32 v198, v187
	s_nop 1
	v_permlane32_swap_b32 v187, v198
	ds_read_b64 v[34:35], v190 offset:55552
	ds_read_b64 v[36:37], v191 offset:55552
	ds_read_b64 v[38:39], v194 offset:55552
	ds_read_b64 v[40:41], v195 offset:55552
	ds_read_b64 v[42:43], v192 offset:55552
	ds_read_b64 v[44:45], v193 offset:55552
	ds_read_b64 v[46:47], v196 offset:55552
	ds_read_b64 v[48:49], v197 offset:55552
	v_max_f32_e32 v88, v187, v198
	v_mov_b32_e32 v188, 0
	v_mov_b32_e32 v189, 0
	v_sub_f32_e32 v102, v102, v88
	v_sub_f32_e32 v103, v103, v88
	v_sub_f32_e32 v104, v104, v88
	v_sub_f32_e32 v105, v105, v88
	v_sub_f32_e32 v106, v106, v88
	v_sub_f32_e32 v107, v107, v88
	v_sub_f32_e32 v108, v108, v88
	v_sub_f32_e32 v109, v109, v88
	v_exp_f32_e32 v102, v102
	v_exp_f32_e32 v103, v103
	v_exp_f32_e32 v104, v104
	v_exp_f32_e32 v105, v105
	v_exp_f32_e32 v106, v106
	v_exp_f32_e32 v107, v107
	v_exp_f32_e32 v108, v108
	v_exp_f32_e32 v109, v109
	v_pk_add_f32 v[188:189], v[188:189], v[102:103]
	v_pk_add_f32 v[188:189], v[188:189], v[104:105]
	v_pk_add_f32 v[188:189], v[188:189], v[106:107]
	v_pk_add_f32 v[188:189], v[188:189], v[108:109]
	v_cvt_pk_bf16_f32 v102, v102, v103
	v_cvt_pk_bf16_f32 v103, v104, v105
	v_cvt_pk_bf16_f32 v104, v106, v107
	v_cvt_pk_bf16_f32 v105, v108, v109
	s_nop 1
	s_waitcnt lgkmcnt(4)
	v_mfma_f32_32x32x16_bf16 v[18:33], v[34:37], v[102:105], 0
	v_mfma_f32_32x32x16_bf16 v[2:17], v[38:41], v[102:105], 0
	ds_read_b64 v[34:35], v190 offset:55616
	ds_read_b64 v[36:37], v191 offset:55616
	ds_read_b64 v[38:39], v194 offset:55616
	ds_read_b64 v[40:41], v195 offset:55616
	v_sub_f32_e32 v110, v110, v88
	v_sub_f32_e32 v111, v111, v88
	v_sub_f32_e32 v112, v112, v88
	v_sub_f32_e32 v113, v113, v88
	v_sub_f32_e32 v114, v114, v88
	v_sub_f32_e32 v115, v115, v88
	v_sub_f32_e32 v116, v116, v88
	v_sub_f32_e32 v117, v117, v88
	v_exp_f32_e32 v110, v110
	v_exp_f32_e32 v111, v111
	v_exp_f32_e32 v112, v112
	v_exp_f32_e32 v113, v113
	v_exp_f32_e32 v114, v114
	v_exp_f32_e32 v115, v115
	v_exp_f32_e32 v116, v116
	v_exp_f32_e32 v117, v117
	v_pk_add_f32 v[188:189], v[188:189], v[110:111]
	v_pk_add_f32 v[188:189], v[188:189], v[112:113]
	v_pk_add_f32 v[188:189], v[188:189], v[114:115]
	v_pk_add_f32 v[188:189], v[188:189], v[116:117]
	v_cvt_pk_bf16_f32 v110, v110, v111
	v_cvt_pk_bf16_f32 v111, v112, v113
	v_cvt_pk_bf16_f32 v112, v114, v115
	v_cvt_pk_bf16_f32 v113, v116, v117
	s_nop 1
	s_waitcnt lgkmcnt(4)
; #define LAS __attribute__((address_space(3)))
; #define MFMA32(a, b, c) __builtin_amdgcn_mfma_f32_32x32x16_bf16((a), (b), (c), 0, 0, 0)
; #define VFRAG2(off) __builtin_shufflevector(*(const LAS s16x4*)(vp + (((off) + 4 * hh) ^ sw)), *(const LAS s16x4*)(vp + (((off) + 8 + 4 * hh) ^ sw)), 0, 1, 2, 3, 4, 5, 6, 7)
; DI void attn_dil_unit(LAS unsigned char* lds, const AttnArgs a) {
;     ...
;     for (int j = 0; j < 5; ++j) {
;         const bf16x8 pb0 = pack8(sc[j], 0), pb1 = pack8(sc[j], 1);
; #pragma unroll
;         for (int d = 0; d < 2; ++d) {
;             const LAS bf16_t* vp = Vl + (d * 32 + r32) * VLD + 32 * wid + 32 * j;
;             const int sw = (((d * 32 + r32) >> 3) & 7) << 2;
;     ...
;             o[d] = MFMA32(VFRAG2(0), pb0, o[d]);
;             o[d] = MFMA32(VFRAG2(16), pb1, o[d]);
	v_mfma_f32_32x32x16_bf16 v[18:33], v[42:45], v[110:113], v[18:33]
	v_mfma_f32_32x32x16_bf16 v[2:17], v[46:49], v[110:113], v[2:17]
	ds_read_b64 v[42:43], v192 offset:55616
	ds_read_b64 v[44:45], v193 offset:55616
	ds_read_b64 v[46:47], v196 offset:55616
	ds_read_b64 v[48:49], v197 offset:55616
	v_sub_f32_e32 v118, v118, v88
	v_sub_f32_e32 v119, v119, v88
	v_sub_f32_e32 v120, v120, v88
	v_sub_f32_e32 v121, v121, v88
	v_sub_f32_e32 v122, v122, v88
	v_sub_f32_e32 v123, v123, v88
	v_sub_f32_e32 v124, v124, v88
	v_sub_f32_e32 v125, v125, v88
	v_exp_f32_e32 v118, v118
	v_exp_f32_e32 v119, v119
	v_exp_f32_e32 v120, v120
	v_exp_f32_e32 v121, v121
	v_exp_f32_e32 v122, v122
	v_exp_f32_e32 v123, v123
	v_exp_f32_e32 v124, v124
	v_exp_f32_e32 v125, v125
	v_pk_add_f32 v[188:189], v[188:189], v[118:119]
	v_pk_add_f32 v[188:189], v[188:189], v[120:121]
	v_pk_add_f32 v[188:189], v[188:189], v[122:123]
	v_pk_add_f32 v[188:189], v[188:189], v[124:125]
	v_cvt_pk_bf16_f32 v118, v118, v119
	v_cvt_pk_bf16_f32 v119, v120, v121
	v_cvt_pk_bf16_f32 v120, v122, v123
	v_cvt_pk_bf16_f32 v121, v124, v125
	s_nop 1
	s_waitcnt lgkmcnt(4)
	v_mfma_f32_32x32x16_bf16 v[18:33], v[34:37], v[118:121], v[18:33]
	v_mfma_f32_32x32x16_bf16 v[2:17], v[38:41], v[118:121], v[2:17]
	ds_read_b64 v[34:35], v190 offset:55680
	ds_read_b64 v[36:37], v191 offset:55680
	ds_read_b64 v[38:39], v194 offset:55680
	ds_read_b64 v[40:41], v195 offset:55680
	v_sub_f32_e32 v126, v126, v88
	v_sub_f32_e32 v127, v127, v88
	v_sub_f32_e32 v128, v128, v88
	v_sub_f32_e32 v129, v129, v88
	v_sub_f32_e32 v130, v130, v88
	v_sub_f32_e32 v131, v131, v88
	v_sub_f32_e32 v132, v132, v88
	v_sub_f32_e32 v133, v133, v88
	v_exp_f32_e32 v126, v126
	v_exp_f32_e32 v127, v127
	v_exp_f32_e32 v128, v128
	v_exp_f32_e32 v129, v129
	v_exp_f32_e32 v130, v130
	v_exp_f32_e32 v131, v131
	v_exp_f32_e32 v132, v132
	v_exp_f32_e32 v133, v133
	v_pk_add_f32 v[188:189], v[188:189], v[126:127]
	v_pk_add_f32 v[188:189], v[188:189], v[128:129]
	v_pk_add_f32 v[188:189], v[188:189], v[130:131]
	v_pk_add_f32 v[188:189], v[188:189], v[132:133]
	v_cvt_pk_bf16_f32 v126, v126, v127
	v_cvt_pk_bf16_f32 v127, v128, v129
	v_cvt_pk_bf16_f32 v128, v130, v131
	v_cvt_pk_bf16_f32 v129, v132, v133
	s_nop 1
	s_waitcnt lgkmcnt(4)
	v_mfma_f32_32x32x16_bf16 v[18:33], v[42:45], v[126:129], v[18:33]
	v_mfma_f32_32x32x16_bf16 v[2:17], v[46:49], v[126:129], v[2:17]
	ds_read_b64 v[42:43], v192 offset:55680
	ds_read_b64 v[44:45], v193 offset:55680
	ds_read_b64 v[46:47], v196 offset:55680
	ds_read_b64 v[48:49], v197 offset:55680
	v_sub_f32_e32 v134, v134, v88
	v_sub_f32_e32 v135, v135, v88
	v_sub_f32_e32 v136, v136, v88
	v_sub_f32_e32 v137, v137, v88
	v_sub_f32_e32 v138, v138, v88
	v_sub_f32_e32 v139, v139, v88
	v_sub_f32_e32 v140, v140, v88
	v_sub_f32_e32 v141, v141, v88
	v_exp_f32_e32 v134, v134
	v_exp_f32_e32 v135, v135
	v_exp_f32_e32 v136, v136
	v_exp_f32_e32 v137, v137
	v_exp_f32_e32 v138, v138
	v_exp_f32_e32 v139, v139
	v_exp_f32_e32 v140, v140
	v_exp_f32_e32 v141, v141
	v_pk_add_f32 v[188:189], v[188:189], v[134:135]
	v_pk_add_f32 v[188:189], v[188:189], v[136:137]
	v_pk_add_f32 v[188:189], v[188:189], v[138:139]
	v_pk_add_f32 v[188:189], v[188:189], v[140:141]
	v_cvt_pk_bf16_f32 v134, v134, v135
	v_cvt_pk_bf16_f32 v135, v136, v137
	v_cvt_pk_bf16_f32 v136, v138, v139
	v_cvt_pk_bf16_f32 v137, v140, v141
	s_nop 1
	s_waitcnt lgkmcnt(4)
	v_mfma_f32_32x32x16_bf16 v[18:33], v[34:37], v[134:137], v[18:33]
	v_mfma_f32_32x32x16_bf16 v[2:17], v[38:41], v[134:137], v[2:17]
	ds_read_b64 v[34:35], v190 offset:55744
	ds_read_b64 v[36:37], v191 offset:55744
	ds_read_b64 v[38:39], v194 offset:55744
	ds_read_b64 v[40:41], v195 offset:55744
	v_sub_f32_e32 v142, v142, v88
	v_sub_f32_e32 v143, v143, v88
	v_sub_f32_e32 v144, v144, v88
	v_sub_f32_e32 v145, v145, v88
	v_sub_f32_e32 v146, v146, v88
	v_sub_f32_e32 v147, v147, v88
	v_sub_f32_e32 v148, v148, v88
	v_sub_f32_e32 v149, v149, v88
	v_exp_f32_e32 v142, v142
	v_exp_f32_e32 v143, v143
	v_exp_f32_e32 v144, v144
	v_exp_f32_e32 v145, v145
	v_exp_f32_e32 v146, v146
	v_exp_f32_e32 v147, v147
	v_exp_f32_e32 v148, v148
	v_exp_f32_e32 v149, v149
	v_pk_add_f32 v[188:189], v[188:189], v[142:143]
	v_pk_add_f32 v[188:189], v[188:189], v[144:145]
	v_pk_add_f32 v[188:189], v[188:189], v[146:147]
	v_pk_add_f32 v[188:189], v[188:189], v[148:149]
	v_cvt_pk_bf16_f32 v142, v142, v143
	v_cvt_pk_bf16_f32 v143, v144, v145
	v_cvt_pk_bf16_f32 v144, v146, v147
	v_cvt_pk_bf16_f32 v145, v148, v149
	s_nop 1
	s_waitcnt lgkmcnt(4)
; #define LAS __attribute__((address_space(3)))
; DI float lg2(float x) { return __builtin_amdgcn_logf(x); }
; #define MFMA32(a, b, c) __builtin_amdgcn_mfma_f32_32x32x16_bf16((a), (b), (c), 0, 0, 0)
; #define VFRAG2(off) __builtin_shufflevector(*(const LAS s16x4*)(vp + (((off) + 4 * hh) ^ sw)), *(const LAS s16x4*)(vp + (((off) + 8 + 4 * hh) ^ sw)), 0, 1, 2, 3, 4, 5, 6, 7)
; DI void attn_dil_unit(LAS unsigned char* lds, const AttnArgs a) {
;     ...
;     for (int j = 0; j < 5; ++j) {
;         const bf16x8 pb0 = pack8(sc[j], 0), pb1 = pack8(sc[j], 1);
; #pragma unroll
;         for (int d = 0; d < 2; ++d) {
;             const LAS bf16_t* vp = Vl + (d * 32 + r32) * VLD + 32 * wid + 32 * j;
;             const int sw = (((d * 32 + r32) >> 3) & 7) << 2;
;     ...
;             o[d] = MFMA32(VFRAG2(0), pb0, o[d]);
;             o[d] = MFMA32(VFRAG2(16), pb1, o[d]);
;     ...
;         }
;     }
;     const float inv = 1.0f / lt;
;     if (hh == 0) a.lse[qtok * a.ldl] = mx + lg2(lt);
	v_mfma_f32_32x32x16_bf16 v[18:33], v[42:45], v[142:145], v[18:33]
	v_mfma_f32_32x32x16_bf16 v[2:17], v[46:49], v[142:145], v[2:17]
	ds_read_b64 v[42:43], v192 offset:55744
	ds_read_b64 v[44:45], v193 offset:55744
	ds_read_b64 v[46:47], v196 offset:55744
	ds_read_b64 v[48:49], v197 offset:55744
	v_sub_f32_e32 v150, v150, v88
	v_sub_f32_e32 v151, v151, v88
	v_sub_f32_e32 v152, v152, v88
	v_sub_f32_e32 v153, v153, v88
	v_sub_f32_e32 v154, v154, v88
	v_sub_f32_e32 v155, v155, v88
	v_sub_f32_e32 v156, v156, v88
	v_sub_f32_e32 v157, v157, v88
	v_exp_f32_e32 v150, v150
	v_exp_f32_e32 v151, v151
	v_exp_f32_e32 v152, v152
	v_exp_f32_e32 v153, v153
	v_exp_f32_e32 v154, v154
	v_exp_f32_e32 v155, v155
	v_exp_f32_e32 v156, v156
	v_exp_f32_e32 v157, v157
	v_pk_add_f32 v[188:189], v[188:189], v[150:151]
	v_pk_add_f32 v[188:189], v[188:189], v[152:153]
	v_pk_add_f32 v[188:189], v[188:189], v[154:155]
	v_pk_add_f32 v[188:189], v[188:189], v[156:157]
	v_cvt_pk_bf16_f32 v150, v150, v151
	v_cvt_pk_bf16_f32 v151, v152, v153
	v_cvt_pk_bf16_f32 v152, v154, v155
	v_cvt_pk_bf16_f32 v153, v156, v157
	s_nop 1
	s_waitcnt lgkmcnt(4)
	v_mfma_f32_32x32x16_bf16 v[18:33], v[34:37], v[150:153], v[18:33]
	v_mfma_f32_32x32x16_bf16 v[2:17], v[38:41], v[150:153], v[2:17]
	ds_read_b64 v[34:35], v190 offset:55808
	ds_read_b64 v[36:37], v191 offset:55808
	ds_read_b64 v[38:39], v194 offset:55808
	ds_read_b64 v[40:41], v195 offset:55808
	v_sub_f32_e32 v158, v158, v88
	v_sub_f32_e32 v159, v159, v88
	v_sub_f32_e32 v160, v160, v88
	v_sub_f32_e32 v161, v161, v88
	v_sub_f32_e32 v162, v162, v88
	v_sub_f32_e32 v163, v163, v88
	v_sub_f32_e32 v164, v164, v88
	v_sub_f32_e32 v165, v165, v88
	v_exp_f32_e32 v158, v158
	v_exp_f32_e32 v159, v159
	v_exp_f32_e32 v160, v160
	v_exp_f32_e32 v161, v161
	v_exp_f32_e32 v162, v162
	v_exp_f32_e32 v163, v163
	v_exp_f32_e32 v164, v164
	v_exp_f32_e32 v165, v165
	v_pk_add_f32 v[188:189], v[188:189], v[158:159]
	v_pk_add_f32 v[188:189], v[188:189], v[160:161]
	v_pk_add_f32 v[188:189], v[188:189], v[162:163]
	v_pk_add_f32 v[188:189], v[188:189], v[164:165]
	v_cvt_pk_bf16_f32 v158, v158, v159
	v_cvt_pk_bf16_f32 v159, v160, v161
	v_cvt_pk_bf16_f32 v160, v162, v163
	v_cvt_pk_bf16_f32 v161, v164, v165
	s_nop 1
	s_waitcnt lgkmcnt(4)
	v_mfma_f32_32x32x16_bf16 v[18:33], v[42:45], v[158:161], v[18:33]
	v_mfma_f32_32x32x16_bf16 v[2:17], v[46:49], v[158:161], v[2:17]
	ds_read_b64 v[42:43], v192 offset:55808
	ds_read_b64 v[44:45], v193 offset:55808
	ds_read_b64 v[46:47], v196 offset:55808
	ds_read_b64 v[48:49], v197 offset:55808
	v_sub_f32_e32 v166, v166, v88
	v_sub_f32_e32 v167, v167, v88
	v_sub_f32_e32 v168, v168, v88
	v_sub_f32_e32 v169, v169, v88
	v_sub_f32_e32 v170, v170, v88
	v_sub_f32_e32 v171, v171, v88
	v_sub_f32_e32 v172, v172, v88
	v_sub_f32_e32 v173, v173, v88
	v_exp_f32_e32 v166, v166
	v_exp_f32_e32 v167, v167
	v_exp_f32_e32 v168, v168
	v_exp_f32_e32 v169, v169
	v_exp_f32_e32 v170, v170
	v_exp_f32_e32 v171, v171
	v_exp_f32_e32 v172, v172
	v_exp_f32_e32 v173, v173
	v_pk_add_f32 v[188:189], v[188:189], v[166:167]
	v_pk_add_f32 v[188:189], v[188:189], v[168:169]
	v_pk_add_f32 v[188:189], v[188:189], v[170:171]
	v_pk_add_f32 v[188:189], v[188:189], v[172:173]
	v_cvt_pk_bf16_f32 v166, v166, v167
	v_cvt_pk_bf16_f32 v167, v168, v169
	v_cvt_pk_bf16_f32 v168, v170, v171
	v_cvt_pk_bf16_f32 v169, v172, v173
	s_nop 1
	s_waitcnt lgkmcnt(4)
	v_mfma_f32_32x32x16_bf16 v[18:33], v[34:37], v[166:169], v[18:33]
	v_mfma_f32_32x32x16_bf16 v[2:17], v[38:41], v[166:169], v[2:17]
	v_sub_f32_e32 v174, v174, v88
	v_sub_f32_e32 v175, v175, v88
	v_sub_f32_e32 v176, v176, v88
	v_sub_f32_e32 v177, v177, v88
	v_sub_f32_e32 v178, v178, v88
	v_sub_f32_e32 v179, v179, v88
	v_sub_f32_e32 v180, v180, v88
	v_sub_f32_e32 v181, v181, v88
	v_exp_f32_e32 v174, v174
	v_exp_f32_e32 v175, v175
	v_exp_f32_e32 v176, v176
	v_exp_f32_e32 v177, v177
	v_exp_f32_e32 v178, v178
	v_exp_f32_e32 v179, v179
	v_exp_f32_e32 v180, v180
	v_exp_f32_e32 v181, v181
	v_pk_add_f32 v[188:189], v[188:189], v[174:175]
	v_pk_add_f32 v[188:189], v[188:189], v[176:177]
	v_pk_add_f32 v[188:189], v[188:189], v[178:179]
	v_pk_add_f32 v[188:189], v[188:189], v[180:181]
	v_cvt_pk_bf16_f32 v174, v174, v175
	v_cvt_pk_bf16_f32 v175, v176, v177
	v_cvt_pk_bf16_f32 v176, v178, v179
	v_cvt_pk_bf16_f32 v177, v180, v181
	s_nop 1
	s_waitcnt lgkmcnt(0)
	v_mfma_f32_32x32x16_bf16 v[18:33], v[42:45], v[174:177], v[18:33]
	v_mfma_f32_32x32x16_bf16 v[2:17], v[46:49], v[174:177], v[2:17]
	v_add_f32_e32 v188, v188, v189
	v_mov_b32_e32 v0, v188
	v_lshlrev_b32_e32 v92, 2, v100
	v_cmp_eq_u32_e32 vcc, 0, v100
	v_permlane32_swap_b32 v188, v0
	v_add_f32_e32 v0, v188, v0
	s_and_saveexec_b64 s[6:7], vcc
	s_cbranch_execz .LBB0_227
	s_lshl_b64 s[0:1], s[14:15], 18
	v_readlane_b32 s4, v255, 9
	v_log_f32_e32 v34, v0
	v_readlane_b32 s5, v255, 10
	s_add_u32 s0, s4, s0
	s_addc_u32 s1, s5, s1
	s_lshl_b32 s4, s21, 2
	s_add_u32 s0, s0, s4
	s_addc_u32 s1, s1, 0
	v_add_f32_e32 v36, v88, v34
	v_lshlrev_b64 v[34:35], 5, v[94:95]
	v_lshl_add_u64 v[34:35], s[0:1], 0, v[34:35]
	global_store_dword v[34:35], v36, off
	s_branch .LBB0_227
